# diff-attention loop: split v_pk_fma_f32/v_pk_add_f32 into scalar v_fma/v_add/v_sub pairs (bit-identical)
# speedup vs baseline: 1.0070x; 1.0035x over previous
.LBB0_362:
	v_cmp_le_i32_e32 vcc, s94, v229
	s_and_saveexec_b64 s[12:13], vcc
	s_cbranch_execz .LBB0_372
	s_bitcmp1_b32 s26, 0
	s_cselect_b32 s0, 0x6c00, 0
	s_add_i32 s0, s0, 0
	v_add_u32_e32 v0, s0, v232
	v_add_u32_e32 v180, v0, v238
	ds_read_b128 v[66:69], v180
	ds_read_b128 v[150:153], v180 offset:32
	ds_read_b128 v[70:73], v180 offset:4608
	ds_read_b128 v[154:157], v180 offset:4640
	s_waitcnt lgkmcnt(3)
	v_mfma_f32_32x32x16_bf16 v[82:97], v[66:69], v[98:101], 0
	s_waitcnt lgkmcnt(1)
	v_mfma_f32_32x32x16_bf16 v[66:81], v[70:73], v[98:101], 0
	v_mfma_f32_32x32x16_bf16 v[82:97], v[150:153], v[102:105], v[82:97]
	ds_read_b128 v[150:153], v180 offset:64
	ds_read_b128 v[158:161], v180 offset:96
	ds_read_b128 v[162:165], v180 offset:4672
	ds_read_b128 v[180:183], v180 offset:4704
	s_waitcnt lgkmcnt(4)
	v_mfma_f32_32x32x16_bf16 v[66:81], v[154:157], v[102:105], v[66:81]
	s_waitcnt lgkmcnt(3)
	v_mfma_f32_32x32x16_bf16 v[82:97], v[150:153], v[106:109], v[82:97]
	v_add_u32_e32 v242, v0, v233
	s_waitcnt lgkmcnt(1)
	v_mfma_f32_32x32x16_bf16 v[66:81], v[162:165], v[106:109], v[66:81]
	v_mfma_f32_32x32x16_bf16 v[82:97], v[158:161], v[110:113], v[82:97]
	ds_read_b128 v[162:165], v242 offset:9216
	ds_read_b128 v[158:161], v242 offset:13824
	ds_read_b128 v[154:157], v242 offset:18432
	ds_read_b128 v[150:153], v242 offset:23040
	s_waitcnt lgkmcnt(4)
	v_mfma_f32_32x32x16_bf16 v[66:81], v[180:183], v[110:113], v[66:81]
	s_movk_i32 s0, 0xbf
	v_add_u32_e32 v180, 0x80, v240
	v_add3_u32 v0, v236, v240, s0
	v_cmp_gt_i32_e32 vcc, s85, v180
	s_and_saveexec_b64 s[0:1], vcc
	s_xor_b64 s[0:1], exec, s[0:1]
	s_cbranch_execz .LBB0_365
	v_add_u32_e32 v181, -1, v0
	v_add_u32_e32 v182, 0x1fe, v0
	v_add_u32_e32 v183, 0x1fd, v0
	v_add_u32_e32 v184, 0x1fc, v0
	v_add_u32_e32 v185, 0x1fb, v0
	v_add_u32_e32 v186, 0x1fa, v0
	v_add_u32_e32 v187, 0x1f9, v0
	v_and_b32_e32 v180, 0x1ff, v0
	s_add_i32 s4, 0, 0x20100
	v_and_b32_e32 v181, 0x1ff, v181
	v_and_b32_e32 v182, 0x1ff, v182
	v_and_b32_e32 v183, 0x1ff, v183
	v_and_b32_e32 v184, 0x1ff, v184
	v_and_b32_e32 v185, 0x1ff, v185
	v_and_b32_e32 v186, 0x1ff, v186
	v_and_b32_e32 v187, 0x1ff, v187
	v_lshl_add_u32 v180, v180, 2, s4
	v_lshl_add_u32 v181, v181, 2, s4
	v_lshl_add_u32 v182, v182, 2, s4
	v_lshl_add_u32 v183, v183, 2, s4
	v_lshl_add_u32 v184, v184, 2, s4
	v_lshl_add_u32 v185, v185, 2, s4
	v_lshl_add_u32 v186, v186, 2, s4
	v_lshl_add_u32 v187, v187, 2, s4
	ds_read_b32 v180, v180
	ds_read_b32 v181, v181
	ds_read_b32 v182, v182
	ds_read_b32 v183, v183
	ds_read_b32 v184, v184
	ds_read_b32 v185, v185
	ds_read_b32 v186, v186
	ds_read_b32 v187, v187
	s_waitcnt lgkmcnt(6)
	v_sub_f32_e32 v180, v180, v178
	v_sub_f32_e32 v181, v181, v178
	s_nop 0
	v_fma_f32 v180, v82, s82, v180
	v_fma_f32 v181, v83, s82, v181
	s_waitcnt lgkmcnt(4)
	v_sub_f32_e32 v82, v182, v178
	v_sub_f32_e32 v83, v183, v178
	v_max3_f32 v188, v180, s33, v181
	v_fma_f32 v182, v84, s82, v82
	v_fma_f32 v183, v85, s82, v83
	s_waitcnt lgkmcnt(2)
	v_sub_f32_e32 v82, v184, v178
	v_sub_f32_e32 v83, v185, v178
	v_max3_f32 v84, v188, v182, v183
	v_fma_f32 v184, v86, s82, v82
	v_fma_f32 v185, v87, s82, v83
	s_waitcnt lgkmcnt(0)
	v_sub_f32_e32 v82, v186, v178
	v_sub_f32_e32 v83, v187, v178
	v_max3_f32 v84, v84, v184, v185
	v_fma_f32 v186, v88, s82, v82
	v_fma_f32 v187, v89, s82, v83
	v_add_u32_e32 v82, 0x1f0, v0
	v_max3_f32 v188, v84, v186, v187
	v_add_u32_e32 v83, 0x1ef, v0
	v_add_u32_e32 v84, 0x1ee, v0
	v_add_u32_e32 v85, 0x1ed, v0
	v_add_u32_e32 v86, 0x1ec, v0
	v_add_u32_e32 v87, 0x1eb, v0
	v_add_u32_e32 v88, 0x1ea, v0
	v_add_u32_e32 v89, 0x1e9, v0
	v_and_b32_e32 v82, 0x1ff, v82
	v_and_b32_e32 v83, 0x1ff, v83
	v_and_b32_e32 v84, 0x1ff, v84
	v_and_b32_e32 v85, 0x1ff, v85
	v_and_b32_e32 v86, 0x1ff, v86
	v_and_b32_e32 v87, 0x1ff, v87
	v_and_b32_e32 v88, 0x1ff, v88
	v_and_b32_e32 v89, 0x1ff, v89
	v_lshl_add_u32 v82, v82, 2, s4
	v_lshl_add_u32 v83, v83, 2, s4
	v_lshl_add_u32 v84, v84, 2, s4
	v_lshl_add_u32 v85, v85, 2, s4
	v_lshl_add_u32 v86, v86, 2, s4
	v_lshl_add_u32 v87, v87, 2, s4
	v_lshl_add_u32 v88, v88, 2, s4
	v_lshl_add_u32 v89, v89, 2, s4
	ds_read_b32 v82, v82
	ds_read_b32 v83, v83
	ds_read_b32 v84, v84
	ds_read_b32 v85, v85
	ds_read_b32 v86, v86
	ds_read_b32 v87, v87
	ds_read_b32 v88, v88
	ds_read_b32 v89, v89
	s_waitcnt lgkmcnt(6)
	v_sub_f32_e32 v82, v82, v178
	v_sub_f32_e32 v83, v83, v178
	s_nop 0
	v_fma_f32 v192, v90, s82, v82
	v_fma_f32 v193, v91, s82, v83
	s_waitcnt lgkmcnt(4)
	v_sub_f32_e32 v82, v84, v178
	v_sub_f32_e32 v83, v85, v178
	v_max3_f32 v90, v188, v192, v193
	v_fma_f32 v206, v92, s82, v82
	v_fma_f32 v207, v93, s82, v83
	s_waitcnt lgkmcnt(2)
	v_sub_f32_e32 v82, v86, v178
	v_sub_f32_e32 v83, v87, v178
	v_max3_f32 v84, v90, v206, v207
	v_fma_f32 v188, v94, s82, v82
	v_fma_f32 v189, v95, s82, v83
	s_waitcnt lgkmcnt(0)
	v_sub_f32_e32 v82, v88, v178
	v_sub_f32_e32 v83, v89, v178
	v_max3_f32 v84, v84, v188, v189
	v_fma_f32 v190, v96, s82, v82
	v_fma_f32 v191, v97, s82, v83
	v_add_u32_e32 v82, 0x1e0, v0
	v_max3_f32 v90, v84, v190, v191
	v_add_u32_e32 v83, 0x1df, v0
	v_add_u32_e32 v84, 0x1de, v0
	v_add_u32_e32 v85, 0x1dd, v0
	v_add_u32_e32 v86, 0x1dc, v0
	v_add_u32_e32 v87, 0x1db, v0
	v_add_u32_e32 v88, 0x1da, v0
	v_add_u32_e32 v89, 0x1d9, v0
	v_and_b32_e32 v82, 0x1ff, v82
	v_and_b32_e32 v83, 0x1ff, v83
	v_and_b32_e32 v84, 0x1ff, v84
	v_and_b32_e32 v85, 0x1ff, v85
	v_and_b32_e32 v86, 0x1ff, v86
	v_and_b32_e32 v87, 0x1ff, v87
	v_and_b32_e32 v88, 0x1ff, v88
	v_and_b32_e32 v89, 0x1ff, v89
	v_lshl_add_u32 v82, v82, 2, s4
	v_lshl_add_u32 v83, v83, 2, s4
	v_lshl_add_u32 v84, v84, 2, s4
	v_lshl_add_u32 v85, v85, 2, s4
	v_lshl_add_u32 v86, v86, 2, s4
	v_lshl_add_u32 v87, v87, 2, s4
	v_lshl_add_u32 v88, v88, 2, s4
	v_lshl_add_u32 v89, v89, 2, s4
	ds_read_b32 v82, v82
	ds_read_b32 v83, v83
	ds_read_b32 v84, v84
	ds_read_b32 v85, v85
	ds_read_b32 v86, v86
	ds_read_b32 v87, v87
	ds_read_b32 v88, v88
	ds_read_b32 v89, v89
	s_waitcnt lgkmcnt(6)
	v_sub_f32_e32 v82, v82, v178
	v_sub_f32_e32 v83, v83, v178
	s_nop 0
	v_fma_f32 v204, v66, s82, v82
	v_fma_f32 v205, v67, s82, v83
	s_waitcnt lgkmcnt(4)
	v_sub_f32_e32 v66, v84, v178
	v_sub_f32_e32 v67, v85, v178
	v_max3_f32 v82, v90, v204, v205
	v_fma_f32 v208, v68, s82, v66
	v_fma_f32 v209, v69, s82, v67
	s_waitcnt lgkmcnt(2)
	v_sub_f32_e32 v66, v86, v178
	v_sub_f32_e32 v67, v87, v178
	v_max3_f32 v68, v82, v208, v209
	v_fma_f32 v210, v70, s82, v66
	v_fma_f32 v211, v71, s82, v67
	s_waitcnt lgkmcnt(0)
	v_sub_f32_e32 v66, v88, v178
	v_sub_f32_e32 v67, v89, v178
	v_max3_f32 v68, v68, v210, v211
	v_fma_f32 v212, v72, s82, v66
	v_fma_f32 v213, v73, s82, v67
	v_add_u32_e32 v66, 0x1d0, v0
	v_max3_f32 v82, v68, v212, v213
	v_add_u32_e32 v67, 0x1cf, v0
	v_add_u32_e32 v68, 0x1ce, v0
	v_add_u32_e32 v69, 0x1cd, v0
	v_add_u32_e32 v70, 0x1cc, v0
	v_add_u32_e32 v71, 0x1cb, v0
	v_add_u32_e32 v72, 0x1ca, v0
	v_and_b32_e32 v66, 0x1ff, v66
	v_and_b32_e32 v67, 0x1ff, v67
	v_and_b32_e32 v68, 0x1ff, v68
	v_and_b32_e32 v69, 0x1ff, v69
	v_and_b32_e32 v70, 0x1ff, v70
	v_and_b32_e32 v71, 0x1ff, v71
	v_and_b32_e32 v72, 0x1ff, v72
	v_add_u32_e32 v0, 0x1c9, v0
	v_lshl_add_u32 v66, v66, 2, s4
	v_lshl_add_u32 v67, v67, 2, s4
	v_lshl_add_u32 v68, v68, 2, s4
	v_lshl_add_u32 v69, v69, 2, s4
	v_lshl_add_u32 v70, v70, 2, s4
	v_lshl_add_u32 v71, v71, 2, s4
	v_lshl_add_u32 v72, v72, 2, s4
	v_and_b32_e32 v0, 0x1ff, v0
	v_lshl_add_u32 v0, v0, 2, s4
	ds_read_b32 v66, v66
	ds_read_b32 v67, v67
	ds_read_b32 v68, v68
	ds_read_b32 v69, v69
	ds_read_b32 v70, v70
	ds_read_b32 v71, v71
	ds_read_b32 v72, v72
	ds_read_b32 v73, v0
	s_waitcnt lgkmcnt(6)
	v_sub_f32_e32 v66, v66, v178
	v_sub_f32_e32 v67, v67, v178
	s_nop 0
	v_fma_f32 v214, v74, s82, v66
	v_fma_f32 v215, v75, s82, v67
	s_waitcnt lgkmcnt(4)
	v_sub_f32_e32 v66, v68, v178
	v_sub_f32_e32 v67, v69, v178
	v_max3_f32 v0, v82, v214, v215
	v_fma_f32 v216, v76, s82, v66
	v_fma_f32 v217, v77, s82, v67
	s_waitcnt lgkmcnt(2)
	v_sub_f32_e32 v66, v70, v178
	v_sub_f32_e32 v67, v71, v178
	v_max3_f32 v0, v0, v216, v217
	v_fma_f32 v218, v78, s82, v66
	v_fma_f32 v219, v79, s82, v67
	s_waitcnt lgkmcnt(0)
	v_sub_f32_e32 v66, v72, v178
	v_sub_f32_e32 v67, v73, v178
	v_max3_f32 v0, v0, v218, v219
	v_fma_f32 v220, v80, s82, v66
	v_fma_f32 v221, v81, s82, v67
	s_nop 0
	v_max3_f32 v243, v0, v220, v221
.LBB0_365:
	s_andn2_saveexec_b64 s[0:1], s[0:1]
	s_cbranch_execz .LBB0_367
	v_fma_f32 v180, v82, s82, v176
	v_fma_f32 v181, v83, s82, v176
	v_fma_f32 v182, v84, s82, v176
	v_fma_f32 v183, v85, s82, v176
	v_max_f32_e32 v0, v180, v181
	v_max_f32_e32 v82, v182, v183
	v_fma_f32 v184, v86, s82, v176
	v_fma_f32 v185, v87, s82, v176
	v_fma_f32 v186, v88, s82, v176
	v_fma_f32 v187, v89, s82, v176
	v_max3_f32 v0, v0, s33, v82
	v_max_f32_e32 v82, v184, v185
	v_max_f32_e32 v83, v186, v187
	v_fma_f32 v192, v90, s82, v176
	v_fma_f32 v193, v91, s82, v176
	v_fma_f32 v206, v92, s82, v176
	v_fma_f32 v207, v93, s82, v176
	v_max3_f32 v0, v0, v82, v83
	v_max_f32_e32 v82, v192, v193
	v_max_f32_e32 v83, v206, v207
	v_fma_f32 v188, v94, s82, v176
	v_fma_f32 v189, v95, s82, v176
	v_fma_f32 v190, v96, s82, v176
	v_fma_f32 v191, v97, s82, v176
	v_max3_f32 v0, v0, v82, v83
	v_max_f32_e32 v82, v188, v189
	v_max_f32_e32 v83, v190, v191
	v_fma_f32 v204, v66, s82, v176
	v_fma_f32 v205, v67, s82, v176
	v_fma_f32 v208, v68, s82, v176
	v_fma_f32 v209, v69, s82, v176
	v_max3_f32 v0, v0, v82, v83
	v_max_f32_e32 v66, v204, v205
	v_max_f32_e32 v67, v208, v209
	v_fma_f32 v210, v70, s82, v176
	v_fma_f32 v211, v71, s82, v176
	v_fma_f32 v212, v72, s82, v176
	v_fma_f32 v213, v73, s82, v176
	v_max3_f32 v0, v0, v66, v67
	v_max_f32_e32 v66, v210, v211
	v_max_f32_e32 v67, v212, v213
	v_fma_f32 v214, v74, s82, v176
	v_fma_f32 v215, v75, s82, v176
	v_fma_f32 v216, v76, s82, v176
	v_fma_f32 v217, v77, s82, v176
	v_max3_f32 v0, v0, v66, v67
	v_max_f32_e32 v66, v214, v215
	v_max_f32_e32 v67, v216, v217
	v_fma_f32 v218, v78, s82, v176
	v_fma_f32 v219, v79, s82, v176
	v_fma_f32 v220, v80, s82, v176
	v_fma_f32 v221, v81, s82, v176
	v_max3_f32 v0, v0, v66, v67
	v_max_f32_e32 v66, v218, v219
	v_max_f32_e32 v67, v220, v221
	v_max3_f32 v243, v0, v66, v67

.LBB0_369:
	s_andn2_b64 vcc, exec, s[14:15]
	v_mov_b32_e32 v0, 1.0
	s_cbranch_vccnz .LBB0_371
	v_mov_b32_e32 v0, v243
	v_mov_b32_e32 v66, v243
	s_nop 1
	v_permlane32_swap_b32_e32 v0, v66
	v_cmp_eq_u32_e32 vcc, v0, v243
	s_nop 1
	v_cndmask_b32_e32 v0, v0, v66, vcc
	v_max_f32_e32 v0, v0, v0
	v_max_f32_e32 v66, v243, v243
	v_max_f32_e32 v0, v66, v0
	v_cmp_lt_f32_e32 vcc, s92, v0
	s_or_b64 vcc, s[0:1], vcc
	s_nop 0
	v_cndmask_b32_e32 v66, 0, v0, vcc
	v_exp_f32_e64 v0, -v66
	v_add_f32_e32 v178, v178, v66
	v_sub_f32_e32 v180, v180, v66
	v_sub_f32_e32 v181, v181, v66
	v_cndmask_b32_e64 v0, v0, 1.0, s[0:1]
	v_pk_mul_f32 v[64:65], v[64:65], v[0:1] op_sel_hi:[1,0]
	v_pk_mul_f32 v[62:63], v[62:63], v[0:1] op_sel_hi:[1,0]
	v_pk_mul_f32 v[60:61], v[60:61], v[0:1] op_sel_hi:[1,0]
	v_pk_mul_f32 v[58:59], v[58:59], v[0:1] op_sel_hi:[1,0]
	v_pk_mul_f32 v[56:57], v[56:57], v[0:1] op_sel_hi:[1,0]
	v_pk_mul_f32 v[54:55], v[54:55], v[0:1] op_sel_hi:[1,0]
	v_pk_mul_f32 v[52:53], v[52:53], v[0:1] op_sel_hi:[1,0]
	v_pk_mul_f32 v[50:51], v[50:51], v[0:1] op_sel_hi:[1,0]
	v_pk_mul_f32 v[48:49], v[48:49], v[0:1] op_sel_hi:[1,0]
	v_pk_mul_f32 v[46:47], v[46:47], v[0:1] op_sel_hi:[1,0]
	v_pk_mul_f32 v[44:45], v[44:45], v[0:1] op_sel_hi:[1,0]
	v_pk_mul_f32 v[42:43], v[42:43], v[0:1] op_sel_hi:[1,0]
	v_pk_mul_f32 v[40:41], v[40:41], v[0:1] op_sel_hi:[1,0]
	v_pk_mul_f32 v[38:39], v[38:39], v[0:1] op_sel_hi:[1,0]
	v_pk_mul_f32 v[36:37], v[36:37], v[0:1] op_sel_hi:[1,0]
	v_pk_mul_f32 v[34:35], v[34:35], v[0:1] op_sel_hi:[1,0]
	v_pk_mul_f32 v[32:33], v[32:33], v[0:1] op_sel_hi:[1,0]
	v_pk_mul_f32 v[30:31], v[30:31], v[0:1] op_sel_hi:[1,0]
	v_pk_mul_f32 v[28:29], v[28:29], v[0:1] op_sel_hi:[1,0]
	v_pk_mul_f32 v[26:27], v[26:27], v[0:1] op_sel_hi:[1,0]
	v_pk_mul_f32 v[24:25], v[24:25], v[0:1] op_sel_hi:[1,0]
	v_pk_mul_f32 v[22:23], v[22:23], v[0:1] op_sel_hi:[1,0]
	v_pk_mul_f32 v[20:21], v[20:21], v[0:1] op_sel_hi:[1,0]
	v_pk_mul_f32 v[18:19], v[18:19], v[0:1] op_sel_hi:[1,0]
	v_pk_mul_f32 v[16:17], v[16:17], v[0:1] op_sel_hi:[1,0]
	v_pk_mul_f32 v[14:15], v[14:15], v[0:1] op_sel_hi:[1,0]
	v_pk_mul_f32 v[12:13], v[12:13], v[0:1] op_sel_hi:[1,0]
	v_pk_mul_f32 v[10:11], v[10:11], v[0:1] op_sel_hi:[1,0]
	v_pk_mul_f32 v[8:9], v[8:9], v[0:1] op_sel_hi:[1,0]
	v_pk_mul_f32 v[6:7], v[6:7], v[0:1] op_sel_hi:[1,0]
	v_pk_mul_f32 v[4:5], v[4:5], v[0:1] op_sel_hi:[1,0]
	v_pk_mul_f32 v[2:3], v[2:3], v[0:1] op_sel_hi:[1,0]
	v_sub_f32_e32 v182, v182, v66
	v_sub_f32_e32 v183, v183, v66
	v_sub_f32_e32 v184, v184, v66
	v_sub_f32_e32 v185, v185, v66
	v_sub_f32_e32 v186, v186, v66
	v_sub_f32_e32 v187, v187, v66
	v_sub_f32_e32 v192, v192, v66
	v_sub_f32_e32 v193, v193, v66
	v_sub_f32_e32 v206, v206, v66
	v_sub_f32_e32 v207, v207, v66
	v_sub_f32_e32 v188, v188, v66
	v_sub_f32_e32 v189, v189, v66
	v_sub_f32_e32 v190, v190, v66
	v_sub_f32_e32 v191, v191, v66
	v_sub_f32_e32 v204, v204, v66
	v_sub_f32_e32 v205, v205, v66
	v_sub_f32_e32 v208, v208, v66
	v_sub_f32_e32 v209, v209, v66
	v_sub_f32_e32 v210, v210, v66
	v_sub_f32_e32 v211, v211, v66
	v_sub_f32_e32 v212, v212, v66
	v_sub_f32_e32 v213, v213, v66
	v_sub_f32_e32 v214, v214, v66
	v_sub_f32_e32 v215, v215, v66
	v_sub_f32_e32 v216, v216, v66
	v_sub_f32_e32 v217, v217, v66
	v_sub_f32_e32 v218, v218, v66
	v_sub_f32_e32 v219, v219, v66
	v_sub_f32_e32 v220, v220, v66
	v_sub_f32_e32 v221, v221, v66
	v_sub_f32_e32 v176, v176, v66
.LBB0_371:
	v_exp_f32_e32 v66, v180
	v_exp_f32_e32 v67, v181
	v_exp_f32_e32 v68, v182
	v_exp_f32_e32 v69, v183
	v_exp_f32_e32 v70, v184
	v_exp_f32_e32 v71, v185
	v_exp_f32_e32 v72, v186
	v_exp_f32_e32 v73, v187
	v_cvt_pk_bf16_f32 v74, v66, v67
	v_cvt_pk_bf16_f32 v75, v68, v69
	v_cvt_pk_bf16_f32 v76, v70, v71
	v_cvt_pk_bf16_f32 v77, v72, v73
	ds_read_b128 v[82:85], v242 offset:9248
	v_exp_f32_e32 v78, v188
	s_waitcnt lgkmcnt(4)
	v_mfma_f32_32x32x16_bf16 v[50:65], v[162:165], v[74:77], v[50:65]
	v_exp_f32_e32 v79, v189
	v_exp_f32_e32 v80, v190
	v_exp_f32_e32 v81, v191
	v_exp_f32_e32 v162, v218
	v_cvt_pk_bf16_f32 v88, v78, v79
	v_exp_f32_e32 v163, v219
	v_cvt_pk_bf16_f32 v89, v80, v81
	s_waitcnt lgkmcnt(3)
	v_mfma_f32_32x32x16_bf16 v[34:49], v[158:161], v[74:77], v[34:49]
	v_exp_f32_e32 v158, v214
	v_exp_f32_e32 v159, v215
	v_exp_f32_e32 v160, v216
	v_exp_f32_e32 v161, v217
	v_exp_f32_e32 v164, v220
	v_exp_f32_e32 v165, v221
	v_add_f32_e32 v66, 0, v66
	v_add_f32_e32 v67, 0, v67
	s_waitcnt lgkmcnt(2)
	v_mfma_f32_32x32x16_bf16 v[18:33], v[154:157], v[74:77], v[18:33]
	v_exp_f32_e32 v154, v210
	v_exp_f32_e32 v155, v211
	v_exp_f32_e32 v156, v212
	v_exp_f32_e32 v157, v213
	v_add_f32_e32 v66, v68, v66
	v_add_f32_e32 v67, v69, v67
	s_nop 0
	v_add_f32_e32 v66, v70, v66
	v_add_f32_e32 v67, v71, v67
	s_waitcnt lgkmcnt(1)
	v_mfma_f32_32x32x16_bf16 v[2:17], v[150:153], v[74:77], v[2:17]
	v_exp_f32_e32 v74, v192
	v_exp_f32_e32 v75, v193
	v_exp_f32_e32 v76, v206
	v_exp_f32_e32 v77, v207
	v_exp_f32_e32 v150, v204
	v_cvt_pk_bf16_f32 v86, v74, v75
	v_exp_f32_e32 v151, v205
	v_cvt_pk_bf16_f32 v87, v76, v77
	v_exp_f32_e32 v152, v208
	v_exp_f32_e32 v153, v209
	s_waitcnt lgkmcnt(0)
	v_mfma_f32_32x32x16_bf16 v[50:65], v[82:85], v[86:89], v[50:65]
	ds_read_b128 v[82:85], v242 offset:13856
	v_add_f32_e64 v66, v72, v66
	v_add_f32_e64 v67, v73, v67
	v_add_f32_e64 v66, v74, v66
	v_add_f32_e64 v67, v75, v67
	v_add_f32_e32 v66, v76, v66
	v_add_f32_e32 v67, v77, v67
	s_waitcnt lgkmcnt(0)
	v_mfma_f32_32x32x16_bf16 v[34:49], v[82:85], v[86:89], v[34:49]
	ds_read_b128 v[82:85], v242 offset:18464
	v_add_f32_e64 v66, v78, v66
	v_add_f32_e64 v67, v79, v67
	v_add_f32_e64 v66, v80, v66
	v_add_f32_e64 v67, v81, v67
	v_add_f32_e32 v66, v150, v66
	v_add_f32_e32 v67, v151, v67
	s_waitcnt lgkmcnt(0)
	v_mfma_f32_32x32x16_bf16 v[18:33], v[82:85], v[86:89], v[18:33]
	ds_read_b128 v[82:85], v242 offset:23072
	ds_read_b128 v[90:93], v242 offset:9280
	v_add_f32_e64 v66, v152, v66
	v_add_f32_e64 v67, v153, v67
	v_add_f32_e64 v66, v154, v66
	v_add_f32_e64 v67, v155, v67
	v_add_f32_e32 v66, v156, v66
	v_add_f32_e32 v67, v157, v67
	s_waitcnt lgkmcnt(1)
	v_mfma_f32_32x32x16_bf16 v[2:17], v[82:85], v[86:89], v[2:17]
	ds_read_b128 v[86:89], v242 offset:13888
	v_cvt_pk_bf16_f32 v82, v150, v151
	v_cvt_pk_bf16_f32 v83, v152, v153
	v_cvt_pk_bf16_f32 v84, v154, v155
	v_cvt_pk_bf16_f32 v85, v156, v157
	v_add_f32_e32 v66, v158, v66
	v_add_f32_e32 v67, v159, v67
	s_waitcnt lgkmcnt(0)
	v_mfma_f32_32x32x16_bf16 v[34:49], v[86:89], v[82:85], v[34:49]
	ds_read_b128 v[86:89], v242 offset:18496
	v_add_f32_e64 v66, v160, v66
	v_add_f32_e64 v67, v161, v67
	v_add_f32_e64 v66, v162, v66
	v_add_f32_e64 v67, v163, v67
	v_add_f32_e32 v66, v164, v66
	v_add_f32_e32 v67, v165, v67
	v_mfma_f32_32x32x16_bf16 v[50:65], v[90:93], v[82:85], v[50:65]
	v_add_f32_e32 v66, v66, v67
	v_fmac_f32_e32 v66, v241, v0
	s_waitcnt lgkmcnt(0)
	v_mfma_f32_32x32x16_bf16 v[18:33], v[86:89], v[82:85], v[18:33]
	ds_read_b128 v[86:89], v242 offset:23104
	ds_read_b128 v[90:93], v242 offset:9312
	s_waitcnt lgkmcnt(1)
	v_mfma_f32_32x32x16_bf16 v[2:17], v[86:89], v[82:85], v[2:17]
	v_cvt_pk_bf16_f32 v82, v158, v159
	v_cvt_pk_bf16_f32 v83, v160, v161
	v_cvt_pk_bf16_f32 v84, v162, v163
	v_cvt_pk_bf16_f32 v85, v164, v165
	s_waitcnt lgkmcnt(0)
	s_nop 0
	v_mfma_f32_32x32x16_bf16 v[50:65], v[90:93], v[82:85], v[50:65]
	ds_read_b128 v[86:89], v242 offset:13920
	ds_read_b128 v[90:93], v242 offset:18528
	ds_read_b128 v[94:97], v242 offset:23136
	s_waitcnt lgkmcnt(2)
	v_mfma_f32_32x32x16_bf16 v[34:49], v[86:89], v[82:85], v[34:49]
	s_waitcnt lgkmcnt(1)
	v_mfma_f32_32x32x16_bf16 v[18:33], v[90:93], v[82:85], v[18:33]
	s_waitcnt lgkmcnt(0)
	v_mfma_f32_32x32x16_bf16 v[2:17], v[94:97], v[82:85], v[2:17]
	v_mov_b32_e32 v241, v66

.LBB0_382:
	v_mov_b32_e32 v0, v243
	v_mov_b32_e32 v66, v243
	s_nop 1
	v_permlane32_swap_b32_e32 v0, v66
	v_cmp_eq_u32_e32 vcc, v0, v243
	s_nop 1
	v_cndmask_b32_e32 v0, v0, v66, vcc
	v_max_f32_e32 v0, v0, v0
	v_max_f32_e32 v66, v243, v243
	v_max_f32_e32 v0, v66, v0
	v_cmp_lt_f32_e32 vcc, s92, v0
	s_nop 1
	v_cndmask_b32_e32 v66, 0, v0, vcc
	v_exp_f32_e64 v0, -v66
	v_add_f32_e32 v178, v178, v66
	v_sub_f32_e32 v180, v180, v66
	v_sub_f32_e32 v181, v181, v66
	v_pk_mul_f32 v[64:65], v[64:65], v[0:1] op_sel_hi:[1,0]
	v_pk_mul_f32 v[62:63], v[62:63], v[0:1] op_sel_hi:[1,0]
	v_pk_mul_f32 v[60:61], v[60:61], v[0:1] op_sel_hi:[1,0]
	v_pk_mul_f32 v[58:59], v[58:59], v[0:1] op_sel_hi:[1,0]
	v_pk_mul_f32 v[56:57], v[56:57], v[0:1] op_sel_hi:[1,0]
	v_pk_mul_f32 v[54:55], v[54:55], v[0:1] op_sel_hi:[1,0]
	v_pk_mul_f32 v[52:53], v[52:53], v[0:1] op_sel_hi:[1,0]
	v_pk_mul_f32 v[50:51], v[50:51], v[0:1] op_sel_hi:[1,0]
	v_pk_mul_f32 v[48:49], v[48:49], v[0:1] op_sel_hi:[1,0]
	v_pk_mul_f32 v[46:47], v[46:47], v[0:1] op_sel_hi:[1,0]
	v_pk_mul_f32 v[44:45], v[44:45], v[0:1] op_sel_hi:[1,0]
	v_pk_mul_f32 v[42:43], v[42:43], v[0:1] op_sel_hi:[1,0]
	v_pk_mul_f32 v[40:41], v[40:41], v[0:1] op_sel_hi:[1,0]
	v_pk_mul_f32 v[38:39], v[38:39], v[0:1] op_sel_hi:[1,0]
	v_pk_mul_f32 v[36:37], v[36:37], v[0:1] op_sel_hi:[1,0]
	v_pk_mul_f32 v[34:35], v[34:35], v[0:1] op_sel_hi:[1,0]
	v_pk_mul_f32 v[32:33], v[32:33], v[0:1] op_sel_hi:[1,0]
	v_pk_mul_f32 v[30:31], v[30:31], v[0:1] op_sel_hi:[1,0]
	v_pk_mul_f32 v[28:29], v[28:29], v[0:1] op_sel_hi:[1,0]
	v_pk_mul_f32 v[26:27], v[26:27], v[0:1] op_sel_hi:[1,0]
	v_pk_mul_f32 v[24:25], v[24:25], v[0:1] op_sel_hi:[1,0]
	v_pk_mul_f32 v[22:23], v[22:23], v[0:1] op_sel_hi:[1,0]
	v_pk_mul_f32 v[20:21], v[20:21], v[0:1] op_sel_hi:[1,0]
	v_pk_mul_f32 v[18:19], v[18:19], v[0:1] op_sel_hi:[1,0]
	v_pk_mul_f32 v[16:17], v[16:17], v[0:1] op_sel_hi:[1,0]
	v_pk_mul_f32 v[14:15], v[14:15], v[0:1] op_sel_hi:[1,0]
	v_pk_mul_f32 v[12:13], v[12:13], v[0:1] op_sel_hi:[1,0]
	v_pk_mul_f32 v[10:11], v[10:11], v[0:1] op_sel_hi:[1,0]
	v_pk_mul_f32 v[8:9], v[8:9], v[0:1] op_sel_hi:[1,0]
	v_pk_mul_f32 v[6:7], v[6:7], v[0:1] op_sel_hi:[1,0]
	v_pk_mul_f32 v[4:5], v[4:5], v[0:1] op_sel_hi:[1,0]
	v_pk_mul_f32 v[2:3], v[2:3], v[0:1] op_sel_hi:[1,0]
	v_sub_f32_e32 v182, v182, v66
	v_sub_f32_e32 v183, v183, v66
	v_sub_f32_e32 v184, v184, v66
	v_sub_f32_e32 v185, v185, v66
	v_sub_f32_e32 v186, v186, v66
	v_sub_f32_e32 v187, v187, v66
	v_sub_f32_e32 v192, v192, v66
	v_sub_f32_e32 v193, v193, v66
	v_sub_f32_e32 v206, v206, v66
	v_sub_f32_e32 v207, v207, v66
	v_sub_f32_e32 v188, v188, v66
	v_sub_f32_e32 v189, v189, v66
	v_sub_f32_e32 v190, v190, v66
	v_sub_f32_e32 v191, v191, v66
	v_sub_f32_e32 v204, v204, v66
	v_sub_f32_e32 v205, v205, v66
	v_sub_f32_e32 v208, v208, v66
	v_sub_f32_e32 v209, v209, v66
	v_sub_f32_e32 v210, v210, v66
	v_sub_f32_e32 v211, v211, v66
	v_sub_f32_e32 v212, v212, v66
	v_sub_f32_e32 v213, v213, v66
	v_sub_f32_e32 v214, v214, v66
	v_sub_f32_e32 v215, v215, v66
	v_sub_f32_e32 v216, v216, v66
	v_sub_f32_e32 v217, v217, v66
	v_sub_f32_e32 v218, v218, v66
	v_sub_f32_e32 v219, v219, v66
	v_sub_f32_e32 v220, v220, v66
	v_sub_f32_e32 v221, v221, v66
	v_sub_f32_e32 v176, v176, v66
	s_branch .LBB0_386
.LBB0_383:
	v_add_u32_e32 v181, -1, v0
	v_add_u32_e32 v182, 0x1fe, v0
	v_add_u32_e32 v183, 0x1fd, v0
	v_add_u32_e32 v184, 0x1fc, v0
	v_add_u32_e32 v185, 0x1fb, v0
	v_add_u32_e32 v186, 0x1fa, v0
	v_add_u32_e32 v187, 0x1f9, v0
	v_and_b32_e32 v180, 0x1ff, v0
	s_add_i32 s4, 0, 0x20100
	v_and_b32_e32 v181, 0x1ff, v181
	v_and_b32_e32 v182, 0x1ff, v182
	v_and_b32_e32 v183, 0x1ff, v183
	v_and_b32_e32 v184, 0x1ff, v184
	v_and_b32_e32 v185, 0x1ff, v185
	v_and_b32_e32 v186, 0x1ff, v186
	v_and_b32_e32 v187, 0x1ff, v187
	v_lshl_add_u32 v180, v180, 2, s4
	v_lshl_add_u32 v181, v181, 2, s4
	v_lshl_add_u32 v182, v182, 2, s4
	v_lshl_add_u32 v183, v183, 2, s4
	v_lshl_add_u32 v184, v184, 2, s4
	v_lshl_add_u32 v185, v185, 2, s4
	v_lshl_add_u32 v186, v186, 2, s4
	v_lshl_add_u32 v187, v187, 2, s4
	ds_read_b32 v180, v180
	ds_read_b32 v181, v181
	ds_read_b32 v182, v182
	ds_read_b32 v183, v183
	ds_read_b32 v184, v184
	ds_read_b32 v185, v185
	ds_read_b32 v186, v186
	ds_read_b32 v187, v187
	s_waitcnt lgkmcnt(6)
	v_sub_f32_e32 v180, v180, v178
	v_sub_f32_e32 v181, v181, v178
	s_nop 0
	v_fma_f32 v180, v82, s82, v180
	v_fma_f32 v181, v83, s82, v181
	s_waitcnt lgkmcnt(4)
	v_sub_f32_e32 v82, v182, v178
	v_sub_f32_e32 v83, v183, v178
	v_max3_f32 v188, v180, s33, v181
	v_fma_f32 v182, v84, s82, v82
	v_fma_f32 v183, v85, s82, v83
	s_waitcnt lgkmcnt(2)
	v_sub_f32_e32 v82, v184, v178
	v_sub_f32_e32 v83, v185, v178
	v_max3_f32 v84, v188, v182, v183
	v_fma_f32 v184, v86, s82, v82
	v_fma_f32 v185, v87, s82, v83
	s_waitcnt lgkmcnt(0)
	v_sub_f32_e32 v82, v186, v178
	v_sub_f32_e32 v83, v187, v178
	v_max3_f32 v84, v84, v184, v185
	v_fma_f32 v186, v88, s82, v82
	v_fma_f32 v187, v89, s82, v83
	v_add_u32_e32 v82, 0x1f0, v0
	v_max3_f32 v188, v84, v186, v187
	v_add_u32_e32 v83, 0x1ef, v0
	v_add_u32_e32 v84, 0x1ee, v0
	v_add_u32_e32 v85, 0x1ed, v0
	v_add_u32_e32 v86, 0x1ec, v0
	v_add_u32_e32 v87, 0x1eb, v0
	v_add_u32_e32 v88, 0x1ea, v0
	v_add_u32_e32 v89, 0x1e9, v0
	v_and_b32_e32 v82, 0x1ff, v82
	v_and_b32_e32 v83, 0x1ff, v83
	v_and_b32_e32 v84, 0x1ff, v84
	v_and_b32_e32 v85, 0x1ff, v85
	v_and_b32_e32 v86, 0x1ff, v86
	v_and_b32_e32 v87, 0x1ff, v87
	v_and_b32_e32 v88, 0x1ff, v88
	v_and_b32_e32 v89, 0x1ff, v89
	v_lshl_add_u32 v82, v82, 2, s4
	v_lshl_add_u32 v83, v83, 2, s4
	v_lshl_add_u32 v84, v84, 2, s4
	v_lshl_add_u32 v85, v85, 2, s4
	v_lshl_add_u32 v86, v86, 2, s4
	v_lshl_add_u32 v87, v87, 2, s4
	v_lshl_add_u32 v88, v88, 2, s4
	v_lshl_add_u32 v89, v89, 2, s4
	ds_read_b32 v82, v82
	ds_read_b32 v83, v83
	ds_read_b32 v84, v84
	ds_read_b32 v85, v85
	ds_read_b32 v86, v86
	ds_read_b32 v87, v87
	ds_read_b32 v88, v88
	ds_read_b32 v89, v89
	s_waitcnt lgkmcnt(6)
	v_sub_f32_e32 v82, v82, v178
	v_sub_f32_e32 v83, v83, v178
	s_nop 0
	v_fma_f32 v192, v90, s82, v82
	v_fma_f32 v193, v91, s82, v83
	s_waitcnt lgkmcnt(4)
	v_sub_f32_e32 v82, v84, v178
	v_sub_f32_e32 v83, v85, v178
	v_max3_f32 v90, v188, v192, v193
	v_fma_f32 v206, v92, s82, v82
	v_fma_f32 v207, v93, s82, v83
	s_waitcnt lgkmcnt(2)
	v_sub_f32_e32 v82, v86, v178
	v_sub_f32_e32 v83, v87, v178
	v_max3_f32 v84, v90, v206, v207
	v_fma_f32 v188, v94, s82, v82
	v_fma_f32 v189, v95, s82, v83
	s_waitcnt lgkmcnt(0)
	v_sub_f32_e32 v82, v88, v178
	v_sub_f32_e32 v83, v89, v178
	v_max3_f32 v84, v84, v188, v189
	v_fma_f32 v190, v96, s82, v82
	v_fma_f32 v191, v97, s82, v83
	v_add_u32_e32 v82, 0x1e0, v0
	v_max3_f32 v90, v84, v190, v191
	v_add_u32_e32 v83, 0x1df, v0
	v_add_u32_e32 v84, 0x1de, v0
	v_add_u32_e32 v85, 0x1dd, v0
	v_add_u32_e32 v86, 0x1dc, v0
	v_add_u32_e32 v87, 0x1db, v0
	v_add_u32_e32 v88, 0x1da, v0
	v_add_u32_e32 v89, 0x1d9, v0
	v_and_b32_e32 v82, 0x1ff, v82
	v_and_b32_e32 v83, 0x1ff, v83
	v_and_b32_e32 v84, 0x1ff, v84
	v_and_b32_e32 v85, 0x1ff, v85
	v_and_b32_e32 v86, 0x1ff, v86
	v_and_b32_e32 v87, 0x1ff, v87
	v_and_b32_e32 v88, 0x1ff, v88
	v_and_b32_e32 v89, 0x1ff, v89
	v_lshl_add_u32 v82, v82, 2, s4
	v_lshl_add_u32 v83, v83, 2, s4
	v_lshl_add_u32 v84, v84, 2, s4
	v_lshl_add_u32 v85, v85, 2, s4
	v_lshl_add_u32 v86, v86, 2, s4
	v_lshl_add_u32 v87, v87, 2, s4
	v_lshl_add_u32 v88, v88, 2, s4
	v_lshl_add_u32 v89, v89, 2, s4
	ds_read_b32 v82, v82
	ds_read_b32 v83, v83
	ds_read_b32 v84, v84
	ds_read_b32 v85, v85
	ds_read_b32 v86, v86
	ds_read_b32 v87, v87
	ds_read_b32 v88, v88
	ds_read_b32 v89, v89
	s_waitcnt lgkmcnt(6)
	v_sub_f32_e32 v82, v82, v178
	v_sub_f32_e32 v83, v83, v178
	s_nop 0
	v_fma_f32 v204, v66, s82, v82
	v_fma_f32 v205, v67, s82, v83
	s_waitcnt lgkmcnt(4)
	v_sub_f32_e32 v66, v84, v178
	v_sub_f32_e32 v67, v85, v178
	v_max3_f32 v82, v90, v204, v205
	v_fma_f32 v208, v68, s82, v66
	v_fma_f32 v209, v69, s82, v67
	s_waitcnt lgkmcnt(2)
	v_sub_f32_e32 v66, v86, v178
	v_sub_f32_e32 v67, v87, v178
	v_max3_f32 v68, v82, v208, v209
	v_fma_f32 v210, v70, s82, v66
	v_fma_f32 v211, v71, s82, v67
	s_waitcnt lgkmcnt(0)
	v_sub_f32_e32 v66, v88, v178
	v_sub_f32_e32 v67, v89, v178
	v_max3_f32 v68, v68, v210, v211
	v_fma_f32 v212, v72, s82, v66
	v_fma_f32 v213, v73, s82, v67
	v_add_u32_e32 v66, 0x1d0, v0
	v_max3_f32 v82, v68, v212, v213
	v_add_u32_e32 v67, 0x1cf, v0
	v_add_u32_e32 v68, 0x1ce, v0
	v_add_u32_e32 v69, 0x1cd, v0
	v_add_u32_e32 v70, 0x1cc, v0
	v_add_u32_e32 v71, 0x1cb, v0
	v_add_u32_e32 v72, 0x1ca, v0
	v_and_b32_e32 v66, 0x1ff, v66
	v_and_b32_e32 v67, 0x1ff, v67
	v_and_b32_e32 v68, 0x1ff, v68
	v_and_b32_e32 v69, 0x1ff, v69
	v_and_b32_e32 v70, 0x1ff, v70
	v_and_b32_e32 v71, 0x1ff, v71
	v_and_b32_e32 v72, 0x1ff, v72
	v_add_u32_e32 v0, 0x1c9, v0
	v_lshl_add_u32 v66, v66, 2, s4
	v_lshl_add_u32 v67, v67, 2, s4
	v_lshl_add_u32 v68, v68, 2, s4
	v_lshl_add_u32 v69, v69, 2, s4
	v_lshl_add_u32 v70, v70, 2, s4
	v_lshl_add_u32 v71, v71, 2, s4
	v_lshl_add_u32 v72, v72, 2, s4
	v_and_b32_e32 v0, 0x1ff, v0
	v_lshl_add_u32 v0, v0, 2, s4
	ds_read_b32 v66, v66
	ds_read_b32 v67, v67
	ds_read_b32 v68, v68
	ds_read_b32 v69, v69
	ds_read_b32 v70, v70
	ds_read_b32 v71, v71
	ds_read_b32 v72, v72
	ds_read_b32 v73, v0
	s_waitcnt lgkmcnt(6)
	v_sub_f32_e32 v66, v66, v178
	v_sub_f32_e32 v67, v67, v178
	s_nop 0
	v_fma_f32 v214, v74, s82, v66
	v_fma_f32 v215, v75, s82, v67
	s_waitcnt lgkmcnt(4)
	v_sub_f32_e32 v66, v68, v178
	v_sub_f32_e32 v67, v69, v178
	v_max3_f32 v0, v82, v214, v215
	v_fma_f32 v216, v76, s82, v66
	v_fma_f32 v217, v77, s82, v67
	s_waitcnt lgkmcnt(2)
	v_sub_f32_e32 v66, v70, v178
	v_sub_f32_e32 v67, v71, v178
	v_max3_f32 v0, v0, v216, v217
	v_fma_f32 v218, v78, s82, v66
	v_fma_f32 v219, v79, s82, v67
	s_waitcnt lgkmcnt(0)
	v_sub_f32_e32 v66, v72, v178
	v_sub_f32_e32 v67, v73, v178
	v_max3_f32 v0, v0, v218, v219
	v_fma_f32 v220, v80, s82, v66
	v_fma_f32 v221, v81, s82, v67
	s_nop 0
	v_max3_f32 v243, v0, v220, v221
	s_andn2_saveexec_b64 s[0:1], s[0:1]
	s_cbranch_execz .LBB0_381
.LBB0_384:
	v_fma_f32 v180, v82, s82, v176
	v_fma_f32 v181, v83, s82, v176
	v_fma_f32 v182, v84, s82, v176
	v_fma_f32 v183, v85, s82, v176
	v_max_f32_e32 v0, v180, v181
	v_max_f32_e32 v82, v182, v183
	v_fma_f32 v184, v86, s82, v176
	v_fma_f32 v185, v87, s82, v176
	v_fma_f32 v186, v88, s82, v176
	v_fma_f32 v187, v89, s82, v176
	v_max3_f32 v0, v0, s33, v82
	v_max_f32_e32 v82, v184, v185
	v_max_f32_e32 v83, v186, v187
	v_fma_f32 v192, v90, s82, v176
	v_fma_f32 v193, v91, s82, v176
	v_fma_f32 v206, v92, s82, v176
	v_fma_f32 v207, v93, s82, v176
	v_max3_f32 v0, v0, v82, v83
	v_max_f32_e32 v82, v192, v193
	v_max_f32_e32 v83, v206, v207
	v_fma_f32 v188, v94, s82, v176
	v_fma_f32 v189, v95, s82, v176
	v_fma_f32 v190, v96, s82, v176
	v_fma_f32 v191, v97, s82, v176
	v_max3_f32 v0, v0, v82, v83
	v_max_f32_e32 v82, v188, v189
	v_max_f32_e32 v83, v190, v191
	v_fma_f32 v204, v66, s82, v176
	v_fma_f32 v205, v67, s82, v176
	v_fma_f32 v208, v68, s82, v176
	v_fma_f32 v209, v69, s82, v176
	v_max3_f32 v0, v0, v82, v83
	v_max_f32_e32 v66, v204, v205
	v_max_f32_e32 v67, v208, v209
	v_fma_f32 v210, v70, s82, v176
	v_fma_f32 v211, v71, s82, v176
	v_fma_f32 v212, v72, s82, v176
	v_fma_f32 v213, v73, s82, v176
	v_max3_f32 v0, v0, v66, v67
	v_max_f32_e32 v66, v210, v211
	v_max_f32_e32 v67, v212, v213
	v_fma_f32 v214, v74, s82, v176
	v_fma_f32 v215, v75, s82, v176
	v_fma_f32 v216, v76, s82, v176
	v_fma_f32 v217, v77, s82, v176
	v_max3_f32 v0, v0, v66, v67
	v_max_f32_e32 v66, v214, v215
	v_max_f32_e32 v67, v216, v217
	v_fma_f32 v218, v78, s82, v176
	v_fma_f32 v219, v79, s82, v176
	v_fma_f32 v220, v80, s82, v176
	v_fma_f32 v221, v81, s82, v176
	v_max3_f32 v0, v0, v66, v67
	v_max_f32_e32 v66, v218, v219
	v_max_f32_e32 v67, v220, v221
	v_max3_f32 v243, v0, v66, v67
	s_or_b64 exec, exec, s[0:1]
	v_cmp_lt_f32_e32 vcc, s92, v243
	s_cbranch_vccnz .LBB0_382

.LBB0_395:
	v_mov_b32_e32 v0, v243
	s_nop 0
	v_mov_b32_e32 v66, v243
	s_nop 1
	v_permlane32_swap_b32_e32 v0, v66
	v_cmp_eq_u32_e32 vcc, v0, v243
	s_nop 1
	v_cndmask_b32_e32 v0, v0, v66, vcc
	v_max_f32_e32 v0, v0, v0
	v_max_f32_e32 v66, v243, v243
	v_max_f32_e32 v0, v66, v0
	v_cmp_lt_f32_e32 vcc, s92, v0
	s_nop 1
	v_cndmask_b32_e32 v66, 0, v0, vcc
	v_exp_f32_e64 v0, -v66
	v_add_f32_e32 v178, v178, v66
	v_sub_f32_e32 v180, v180, v66
	v_sub_f32_e32 v181, v181, v66
	v_pk_mul_f32 v[64:65], v[64:65], v[0:1] op_sel_hi:[1,0]
	v_pk_mul_f32 v[62:63], v[62:63], v[0:1] op_sel_hi:[1,0]
	v_pk_mul_f32 v[60:61], v[60:61], v[0:1] op_sel_hi:[1,0]
	v_pk_mul_f32 v[58:59], v[58:59], v[0:1] op_sel_hi:[1,0]
	v_pk_mul_f32 v[56:57], v[56:57], v[0:1] op_sel_hi:[1,0]
	v_pk_mul_f32 v[54:55], v[54:55], v[0:1] op_sel_hi:[1,0]
	v_pk_mul_f32 v[52:53], v[52:53], v[0:1] op_sel_hi:[1,0]
	v_pk_mul_f32 v[50:51], v[50:51], v[0:1] op_sel_hi:[1,0]
	v_pk_mul_f32 v[48:49], v[48:49], v[0:1] op_sel_hi:[1,0]
	v_pk_mul_f32 v[46:47], v[46:47], v[0:1] op_sel_hi:[1,0]
	v_pk_mul_f32 v[44:45], v[44:45], v[0:1] op_sel_hi:[1,0]
	v_pk_mul_f32 v[42:43], v[42:43], v[0:1] op_sel_hi:[1,0]
	v_pk_mul_f32 v[40:41], v[40:41], v[0:1] op_sel_hi:[1,0]
	v_pk_mul_f32 v[38:39], v[38:39], v[0:1] op_sel_hi:[1,0]
	v_pk_mul_f32 v[36:37], v[36:37], v[0:1] op_sel_hi:[1,0]
	v_pk_mul_f32 v[34:35], v[34:35], v[0:1] op_sel_hi:[1,0]
	v_pk_mul_f32 v[32:33], v[32:33], v[0:1] op_sel_hi:[1,0]
	v_pk_mul_f32 v[30:31], v[30:31], v[0:1] op_sel_hi:[1,0]
	v_pk_mul_f32 v[28:29], v[28:29], v[0:1] op_sel_hi:[1,0]
	v_pk_mul_f32 v[26:27], v[26:27], v[0:1] op_sel_hi:[1,0]
	v_pk_mul_f32 v[24:25], v[24:25], v[0:1] op_sel_hi:[1,0]
	v_pk_mul_f32 v[22:23], v[22:23], v[0:1] op_sel_hi:[1,0]
	v_pk_mul_f32 v[20:21], v[20:21], v[0:1] op_sel_hi:[1,0]
	v_pk_mul_f32 v[18:19], v[18:19], v[0:1] op_sel_hi:[1,0]
	v_pk_mul_f32 v[16:17], v[16:17], v[0:1] op_sel_hi:[1,0]
	v_pk_mul_f32 v[14:15], v[14:15], v[0:1] op_sel_hi:[1,0]
	v_pk_mul_f32 v[12:13], v[12:13], v[0:1] op_sel_hi:[1,0]
	v_pk_mul_f32 v[10:11], v[10:11], v[0:1] op_sel_hi:[1,0]
	v_pk_mul_f32 v[8:9], v[8:9], v[0:1] op_sel_hi:[1,0]
	v_pk_mul_f32 v[6:7], v[6:7], v[0:1] op_sel_hi:[1,0]
	v_pk_mul_f32 v[4:5], v[4:5], v[0:1] op_sel_hi:[1,0]
	v_pk_mul_f32 v[2:3], v[2:3], v[0:1] op_sel_hi:[1,0]
	v_sub_f32_e32 v182, v182, v66
	v_sub_f32_e32 v183, v183, v66
	v_sub_f32_e32 v184, v184, v66
	v_sub_f32_e32 v185, v185, v66
	v_sub_f32_e32 v186, v186, v66
	v_sub_f32_e32 v187, v187, v66
	v_sub_f32_e32 v192, v192, v66
	v_sub_f32_e32 v193, v193, v66
	v_sub_f32_e32 v206, v206, v66
	v_sub_f32_e32 v207, v207, v66
	v_sub_f32_e32 v188, v188, v66
	v_sub_f32_e32 v189, v189, v66
	v_sub_f32_e32 v190, v190, v66
	v_sub_f32_e32 v191, v191, v66
	v_sub_f32_e32 v204, v204, v66
	v_sub_f32_e32 v205, v205, v66
	v_sub_f32_e32 v208, v208, v66
	v_sub_f32_e32 v209, v209, v66
	v_sub_f32_e32 v210, v210, v66
	v_sub_f32_e32 v211, v211, v66
	v_sub_f32_e32 v212, v212, v66
	v_sub_f32_e32 v213, v213, v66
	v_sub_f32_e32 v214, v214, v66
	v_sub_f32_e32 v215, v215, v66
	v_sub_f32_e32 v216, v216, v66
	v_sub_f32_e32 v217, v217, v66
	v_sub_f32_e32 v218, v218, v66
	v_sub_f32_e32 v219, v219, v66
	v_sub_f32_e32 v220, v220, v66
	v_sub_f32_e32 v221, v221, v66
	v_sub_f32_e32 v176, v176, v66
	s_branch .LBB0_399

.LBB0_399:
	s_nop 0
	v_exp_f32_e32 v66, v180
	v_exp_f32_e32 v67, v181
	v_exp_f32_e32 v68, v182
	v_exp_f32_e32 v69, v183
	v_exp_f32_e32 v70, v184
	v_exp_f32_e32 v71, v185
	v_exp_f32_e32 v72, v186
	v_exp_f32_e32 v73, v187
	v_cvt_pk_bf16_f32 v74, v66, v67
	v_cvt_pk_bf16_f32 v75, v68, v69
	v_cvt_pk_bf16_f32 v76, v70, v71
	v_cvt_pk_bf16_f32 v77, v72, v73
	ds_read_b128 v[82:85], v242 offset:9248
	v_exp_f32_e32 v78, v188
	s_waitcnt lgkmcnt(4)
	v_mfma_f32_32x32x16_bf16 v[50:65], v[162:165], v[74:77], v[50:65]
	v_exp_f32_e32 v79, v189
	v_exp_f32_e32 v80, v190
	v_exp_f32_e32 v81, v191
	v_exp_f32_e32 v162, v218
	v_cvt_pk_bf16_f32 v88, v78, v79
	v_exp_f32_e32 v163, v219
	v_cvt_pk_bf16_f32 v89, v80, v81
	s_waitcnt lgkmcnt(3)
	v_mfma_f32_32x32x16_bf16 v[34:49], v[158:161], v[74:77], v[34:49]
	v_exp_f32_e32 v158, v214
	v_exp_f32_e32 v159, v215
	v_exp_f32_e32 v160, v216
	v_exp_f32_e32 v161, v217
	v_exp_f32_e32 v164, v220
	v_exp_f32_e32 v165, v221
	v_add_f32_e32 v66, 0, v66
	v_add_f32_e32 v67, 0, v67
	s_waitcnt lgkmcnt(2)
	v_mfma_f32_32x32x16_bf16 v[18:33], v[154:157], v[74:77], v[18:33]
	v_exp_f32_e32 v154, v210
	v_exp_f32_e32 v155, v211
	v_exp_f32_e32 v156, v212
	v_exp_f32_e32 v157, v213
	v_add_f32_e32 v66, v68, v66
	v_add_f32_e32 v67, v69, v67
	s_nop 0
	v_add_f32_e32 v66, v70, v66
	v_add_f32_e32 v67, v71, v67
	s_waitcnt lgkmcnt(1)
	v_mfma_f32_32x32x16_bf16 v[2:17], v[150:153], v[74:77], v[2:17]
	v_exp_f32_e32 v74, v192
	v_exp_f32_e32 v75, v193
	v_exp_f32_e32 v76, v206
	v_exp_f32_e32 v77, v207
	v_exp_f32_e32 v150, v204
	v_cvt_pk_bf16_f32 v86, v74, v75
	v_exp_f32_e32 v151, v205
	v_cvt_pk_bf16_f32 v87, v76, v77
	v_exp_f32_e32 v152, v208
	v_exp_f32_e32 v153, v209
	s_waitcnt lgkmcnt(0)
	v_mfma_f32_32x32x16_bf16 v[50:65], v[82:85], v[86:89], v[50:65]
	ds_read_b128 v[82:85], v242 offset:13856
	v_add_f32_e64 v66, v72, v66
	v_add_f32_e64 v67, v73, v67
	v_add_f32_e64 v66, v74, v66
	v_add_f32_e64 v67, v75, v67
	v_add_f32_e32 v66, v76, v66
	v_add_f32_e32 v67, v77, v67
	s_waitcnt lgkmcnt(0)
	v_mfma_f32_32x32x16_bf16 v[34:49], v[82:85], v[86:89], v[34:49]
	ds_read_b128 v[82:85], v242 offset:18464
	v_add_f32_e64 v66, v78, v66
	v_add_f32_e64 v67, v79, v67
	v_add_f32_e64 v66, v80, v66
	v_add_f32_e64 v67, v81, v67
	v_add_f32_e32 v66, v150, v66
	v_add_f32_e32 v67, v151, v67
	s_waitcnt lgkmcnt(0)
	v_mfma_f32_32x32x16_bf16 v[18:33], v[82:85], v[86:89], v[18:33]
	ds_read_b128 v[82:85], v242 offset:23072
	ds_read_b128 v[90:93], v242 offset:9280
	v_add_f32_e64 v66, v152, v66
	v_add_f32_e64 v67, v153, v67
	v_add_f32_e64 v66, v154, v66
	v_add_f32_e64 v67, v155, v67
	v_add_f32_e32 v66, v156, v66
	v_add_f32_e32 v67, v157, v67
	s_waitcnt lgkmcnt(1)
	v_mfma_f32_32x32x16_bf16 v[2:17], v[82:85], v[86:89], v[2:17]
	ds_read_b128 v[86:89], v242 offset:13888
	v_cvt_pk_bf16_f32 v82, v150, v151
	v_cvt_pk_bf16_f32 v83, v152, v153
	v_cvt_pk_bf16_f32 v84, v154, v155
	v_cvt_pk_bf16_f32 v85, v156, v157
	v_add_f32_e32 v66, v158, v66
	v_add_f32_e32 v67, v159, v67
	s_waitcnt lgkmcnt(0)
	v_mfma_f32_32x32x16_bf16 v[34:49], v[86:89], v[82:85], v[34:49]
	ds_read_b128 v[86:89], v242 offset:18496
	v_add_f32_e64 v66, v160, v66
	v_add_f32_e64 v67, v161, v67
	v_add_f32_e64 v66, v162, v66
	v_add_f32_e64 v67, v163, v67
	v_add_f32_e32 v66, v164, v66
	v_add_f32_e32 v67, v165, v67
	v_mfma_f32_32x32x16_bf16 v[50:65], v[90:93], v[82:85], v[50:65]
	v_add_f32_e32 v66, v66, v67
	v_fmac_f32_e32 v66, v241, v0
	s_waitcnt lgkmcnt(0)
	v_mfma_f32_32x32x16_bf16 v[18:33], v[86:89], v[82:85], v[18:33]
	ds_read_b128 v[86:89], v242 offset:23104
	ds_read_b128 v[90:93], v242 offset:9312
	s_waitcnt lgkmcnt(1)
	v_mfma_f32_32x32x16_bf16 v[2:17], v[86:89], v[82:85], v[2:17]
	v_cvt_pk_bf16_f32 v82, v158, v159
	v_cvt_pk_bf16_f32 v83, v160, v161
	v_cvt_pk_bf16_f32 v84, v162, v163
	v_cvt_pk_bf16_f32 v85, v164, v165
	s_waitcnt lgkmcnt(0)
	s_nop 0
	v_mfma_f32_32x32x16_bf16 v[50:65], v[90:93], v[82:85], v[50:65]
	ds_read_b128 v[86:89], v242 offset:13920
	ds_read_b128 v[90:93], v242 offset:18528
	ds_read_b128 v[94:97], v242 offset:23136
	s_waitcnt lgkmcnt(2)
	v_mfma_f32_32x32x16_bf16 v[34:49], v[86:89], v[82:85], v[34:49]
	s_waitcnt lgkmcnt(1)
	v_mfma_f32_32x32x16_bf16 v[18:33], v[90:93], v[82:85], v[18:33]
	s_waitcnt lgkmcnt(0)
	v_mfma_f32_32x32x16_bf16 v[2:17], v[94:97], v[82:85], v[2:17]
	v_mov_b32_e32 v241, v66
